# nt (streaming) policy on the final output stores of the last GEMM phase; plus earlier fetch/hoist edits
# speedup vs baseline: 1.0064x; 1.0064x over previous
.LBB0_1508:
	v_lshl_add_u32 v144, s28, 8, v146
	v_lshl_or_b32 v142, s53, 8, v148
	v_ashrrev_i32_e32 v145, 31, v144
	v_ashrrev_i32_e32 v143, 31, v142
	v_lshlrev_b64 v[140:141], 11, v[144:145]
	v_lshl_add_u64 v[140:141], v[140:141], 0, v[142:143]
	v_lshl_add_u64 v[152:153], v[140:141], 1, s[4:5]
	global_load_dwordx2 v[154:155], v[152:153], off
	v_lshl_add_u64 v[156:157], v[140:141], 2, s[82:83]
	s_andn2_b64 vcc, exec, s[0:1]
	s_mov_b64 s[0:1], -1
	s_waitcnt vmcnt(0)
	v_lshlrev_b32_e32 v158, 16, v154
	v_and_b32_e32 v159, 0xffff0000, v154
	v_lshlrev_b32_e32 v154, 16, v155
	v_and_b32_e32 v155, 0xffff0000, v155
	v_pk_add_f32 v[126:127], v[126:127], v[154:155]
	v_pk_add_f32 v[124:125], v[124:125], v[158:159]
	global_store_dwordx4 v[156:157], v[124:127], off nt
	global_load_dwordx2 v[124:125], v[152:153], off offset:32
	s_waitcnt vmcnt(0)
	v_lshlrev_b32_e32 v126, 16, v124
	v_and_b32_e32 v127, 0xffff0000, v124
	v_lshlrev_b32_e32 v124, 16, v125
	v_and_b32_e32 v125, 0xffff0000, v125
	v_pk_add_f32 v[122:123], v[122:123], v[124:125]
	v_pk_add_f32 v[120:121], v[120:121], v[126:127]
	global_store_dwordx4 v[156:157], v[120:123], off offset:64 nt
	global_load_dwordx2 v[120:121], v[152:153], off offset:256
	s_waitcnt vmcnt(0)
	v_lshlrev_b32_e32 v122, 16, v120
	v_and_b32_e32 v123, 0xffff0000, v120
	v_lshlrev_b32_e32 v120, 16, v121
	v_and_b32_e32 v121, 0xffff0000, v121
	v_pk_add_f32 v[118:119], v[118:119], v[120:121]
	v_pk_add_f32 v[116:117], v[116:117], v[122:123]
	global_store_dwordx4 v[156:157], v[116:119], off offset:512 nt
	global_load_dwordx2 v[116:117], v[152:153], off offset:288
	s_waitcnt vmcnt(0)
	v_lshlrev_b32_e32 v122, 16, v116
	v_or_b32_e32 v118, 16, v144
	v_ashrrev_i32_e32 v119, 31, v118
	v_lshlrev_b64 v[118:119], 11, v[118:119]
	v_and_b32_e32 v123, 0xffff0000, v116
	v_lshlrev_b32_e32 v116, 16, v117
	v_and_b32_e32 v117, 0xffff0000, v117
	v_lshl_add_u64 v[118:119], v[118:119], 0, v[142:143]
	v_pk_add_f32 v[110:111], v[110:111], v[116:117]
	v_pk_add_f32 v[108:109], v[108:109], v[122:123]
	v_lshl_add_u64 v[120:121], v[118:119], 1, s[4:5]
	global_store_dwordx4 v[156:157], v[108:111], off offset:576 nt
	global_load_dwordx2 v[108:109], v[120:121], off
	v_lshl_add_u64 v[116:117], v[118:119], 2, s[82:83]
	s_waitcnt vmcnt(0)
	v_lshlrev_b32_e32 v118, 16, v108
	v_and_b32_e32 v119, 0xffff0000, v108
	v_lshlrev_b32_e32 v108, 16, v109
	v_and_b32_e32 v109, 0xffff0000, v109
	v_pk_add_f32 v[110:111], v[114:115], v[108:109]
	v_pk_add_f32 v[108:109], v[112:113], v[118:119]
	global_store_dwordx4 v[116:117], v[108:111], off nt
	global_load_dwordx2 v[108:109], v[120:121], off offset:32
	s_waitcnt vmcnt(0)
	v_lshlrev_b32_e32 v110, 16, v108
	v_and_b32_e32 v111, 0xffff0000, v108
	v_lshlrev_b32_e32 v108, 16, v109
	v_and_b32_e32 v109, 0xffff0000, v109
	v_pk_add_f32 v[106:107], v[106:107], v[108:109]
	v_pk_add_f32 v[104:105], v[104:105], v[110:111]
	global_store_dwordx4 v[116:117], v[104:107], off offset:64 nt
	global_load_dwordx2 v[104:105], v[120:121], off offset:256
	s_waitcnt vmcnt(0)
	v_lshlrev_b32_e32 v106, 16, v104
	v_and_b32_e32 v107, 0xffff0000, v104
	v_lshlrev_b32_e32 v104, 16, v105
	v_and_b32_e32 v105, 0xffff0000, v105
	v_pk_add_f32 v[102:103], v[102:103], v[104:105]
	v_pk_add_f32 v[100:101], v[100:101], v[106:107]
	global_store_dwordx4 v[116:117], v[100:103], off offset:512 nt
	global_load_dwordx2 v[100:101], v[120:121], off offset:288
	s_waitcnt vmcnt(0)
	v_lshlrev_b32_e32 v106, 16, v100
	v_or_b32_e32 v102, 32, v144
	v_ashrrev_i32_e32 v103, 31, v102
	v_lshlrev_b64 v[102:103], 11, v[102:103]
	v_and_b32_e32 v107, 0xffff0000, v100
	v_lshlrev_b32_e32 v100, 16, v101
	v_and_b32_e32 v101, 0xffff0000, v101
	v_lshl_add_u64 v[102:103], v[102:103], 0, v[142:143]
	v_pk_add_f32 v[94:95], v[94:95], v[100:101]
	v_pk_add_f32 v[92:93], v[92:93], v[106:107]
	v_lshl_add_u64 v[104:105], v[102:103], 1, s[4:5]
	global_store_dwordx4 v[116:117], v[92:95], off offset:576 nt
	global_load_dwordx2 v[92:93], v[104:105], off
	v_lshl_add_u64 v[100:101], v[102:103], 2, s[82:83]
	s_waitcnt vmcnt(0)
	v_lshlrev_b32_e32 v102, 16, v92
	v_and_b32_e32 v103, 0xffff0000, v92
	v_lshlrev_b32_e32 v92, 16, v93
	v_and_b32_e32 v93, 0xffff0000, v93
	v_pk_add_f32 v[94:95], v[98:99], v[92:93]
	v_pk_add_f32 v[92:93], v[96:97], v[102:103]
	global_store_dwordx4 v[100:101], v[92:95], off nt
	global_load_dwordx2 v[92:93], v[104:105], off offset:32
	s_waitcnt vmcnt(0)
	v_lshlrev_b32_e32 v94, 16, v92
	v_and_b32_e32 v95, 0xffff0000, v92
	v_lshlrev_b32_e32 v92, 16, v93
	v_and_b32_e32 v93, 0xffff0000, v93
	v_pk_add_f32 v[90:91], v[90:91], v[92:93]
	v_pk_add_f32 v[88:89], v[88:89], v[94:95]
	global_store_dwordx4 v[100:101], v[88:91], off offset:64 nt
	global_load_dwordx2 v[88:89], v[104:105], off offset:256
	s_waitcnt vmcnt(0)
	v_lshlrev_b32_e32 v90, 16, v88
	v_and_b32_e32 v91, 0xffff0000, v88
	v_lshlrev_b32_e32 v88, 16, v89
	v_and_b32_e32 v89, 0xffff0000, v89
	v_pk_add_f32 v[86:87], v[86:87], v[88:89]
	v_pk_add_f32 v[84:85], v[84:85], v[90:91]
	global_store_dwordx4 v[100:101], v[84:87], off offset:512 nt
	global_load_dwordx2 v[84:85], v[104:105], off offset:288
	s_waitcnt vmcnt(0)
	v_lshlrev_b32_e32 v90, 16, v84
	v_or_b32_e32 v86, 48, v144
	v_ashrrev_i32_e32 v87, 31, v86
	v_lshlrev_b64 v[86:87], 11, v[86:87]
	v_and_b32_e32 v91, 0xffff0000, v84
	v_lshlrev_b32_e32 v84, 16, v85
	v_and_b32_e32 v85, 0xffff0000, v85
	v_lshl_add_u64 v[86:87], v[86:87], 0, v[142:143]
	v_pk_add_f32 v[78:79], v[78:79], v[84:85]
	v_pk_add_f32 v[76:77], v[76:77], v[90:91]
	v_lshl_add_u64 v[88:89], v[86:87], 1, s[4:5]
	global_store_dwordx4 v[100:101], v[76:79], off offset:576 nt
	global_load_dwordx2 v[76:77], v[88:89], off
	v_lshl_add_u64 v[84:85], v[86:87], 2, s[82:83]
	s_waitcnt vmcnt(0)
	v_lshlrev_b32_e32 v86, 16, v76
	v_and_b32_e32 v87, 0xffff0000, v76
	v_lshlrev_b32_e32 v76, 16, v77
	v_and_b32_e32 v77, 0xffff0000, v77
	v_pk_add_f32 v[78:79], v[82:83], v[76:77]
	v_pk_add_f32 v[76:77], v[80:81], v[86:87]
	global_store_dwordx4 v[84:85], v[76:79], off nt
	global_load_dwordx2 v[76:77], v[88:89], off offset:32
	s_waitcnt vmcnt(0)
	v_lshlrev_b32_e32 v78, 16, v76
	v_and_b32_e32 v79, 0xffff0000, v76
	v_lshlrev_b32_e32 v76, 16, v77
	v_and_b32_e32 v77, 0xffff0000, v77
	v_pk_add_f32 v[74:75], v[74:75], v[76:77]
	v_pk_add_f32 v[72:73], v[72:73], v[78:79]
	global_store_dwordx4 v[84:85], v[72:75], off offset:64 nt
	global_load_dwordx2 v[72:73], v[88:89], off offset:256
	s_waitcnt vmcnt(0)
	v_lshlrev_b32_e32 v74, 16, v72
	v_and_b32_e32 v75, 0xffff0000, v72
	v_lshlrev_b32_e32 v72, 16, v73
	v_and_b32_e32 v73, 0xffff0000, v73
	v_pk_add_f32 v[70:71], v[70:71], v[72:73]
	v_pk_add_f32 v[68:69], v[68:69], v[74:75]
	global_store_dwordx4 v[84:85], v[68:71], off offset:512 nt
	global_load_dwordx2 v[68:69], v[88:89], off offset:288
	s_waitcnt vmcnt(0)
	v_lshlrev_b32_e32 v74, 16, v68
	v_and_b32_e32 v75, 0xffff0000, v68
	v_lshlrev_b32_e32 v68, 16, v69
	v_and_b32_e32 v69, 0xffff0000, v69
	v_lshl_add_u64 v[70:71], v[140:141], 0, s[10:11]
	v_pk_add_f32 v[66:67], v[66:67], v[68:69]
	v_pk_add_f32 v[64:65], v[64:65], v[74:75]
	v_lshl_add_u64 v[72:73], v[70:71], 1, s[4:5]
	global_store_dwordx4 v[84:85], v[64:67], off offset:576 nt
	global_load_dwordx2 v[64:65], v[72:73], off
	s_waitcnt vmcnt(0)
	v_lshlrev_b32_e32 v68, 16, v64
	v_and_b32_e32 v69, 0xffff0000, v64
	v_lshlrev_b32_e32 v64, 16, v65
	v_and_b32_e32 v65, 0xffff0000, v65
	v_lshl_add_u64 v[66:67], v[70:71], 2, s[82:83]
	v_pk_add_f32 v[62:63], v[62:63], v[64:65]
	v_pk_add_f32 v[60:61], v[60:61], v[68:69]
	global_store_dwordx4 v[66:67], v[60:63], off nt
	global_load_dwordx2 v[60:61], v[72:73], off offset:32
	s_waitcnt vmcnt(0)
	v_lshlrev_b32_e32 v62, 16, v60
	v_and_b32_e32 v63, 0xffff0000, v60
	v_lshlrev_b32_e32 v60, 16, v61
	v_and_b32_e32 v61, 0xffff0000, v61
	v_pk_add_f32 v[58:59], v[58:59], v[60:61]
	v_pk_add_f32 v[56:57], v[56:57], v[62:63]
	global_store_dwordx4 v[66:67], v[56:59], off offset:64 nt
	global_load_dwordx2 v[56:57], v[72:73], off offset:256
	s_waitcnt vmcnt(0)
	v_lshlrev_b32_e32 v58, 16, v56
	v_and_b32_e32 v59, 0xffff0000, v56
	v_lshlrev_b32_e32 v56, 16, v57
	v_and_b32_e32 v57, 0xffff0000, v57
	v_pk_add_f32 v[54:55], v[54:55], v[56:57]
	v_pk_add_f32 v[52:53], v[52:53], v[58:59]
	global_store_dwordx4 v[66:67], v[52:55], off offset:512 nt
	global_load_dwordx2 v[52:53], v[72:73], off offset:288
	s_waitcnt vmcnt(0)
	v_lshlrev_b32_e32 v58, 16, v52
	v_and_b32_e32 v59, 0xffff0000, v52
	v_lshlrev_b32_e32 v52, 16, v53
	v_and_b32_e32 v53, 0xffff0000, v53
	v_lshl_add_u64 v[54:55], v[140:141], 0, s[12:13]
	v_pk_add_f32 v[46:47], v[46:47], v[52:53]
	v_pk_add_f32 v[44:45], v[44:45], v[58:59]
	v_lshl_add_u64 v[56:57], v[54:55], 1, s[4:5]
	global_store_dwordx4 v[66:67], v[44:47], off offset:576 nt
	global_load_dwordx2 v[44:45], v[56:57], off
	v_lshl_add_u64 v[52:53], v[54:55], 2, s[82:83]
	s_waitcnt vmcnt(0)
	v_lshlrev_b32_e32 v54, 16, v44
	v_and_b32_e32 v55, 0xffff0000, v44
	v_lshlrev_b32_e32 v44, 16, v45
	v_and_b32_e32 v45, 0xffff0000, v45
	v_pk_add_f32 v[46:47], v[50:51], v[44:45]
	v_pk_add_f32 v[44:45], v[48:49], v[54:55]
	global_store_dwordx4 v[52:53], v[44:47], off nt
	global_load_dwordx2 v[44:45], v[56:57], off offset:32
	s_waitcnt vmcnt(0)
	v_lshlrev_b32_e32 v46, 16, v44
	v_and_b32_e32 v47, 0xffff0000, v44
	v_lshlrev_b32_e32 v44, 16, v45
	v_and_b32_e32 v45, 0xffff0000, v45
	v_pk_add_f32 v[42:43], v[42:43], v[44:45]
	v_pk_add_f32 v[40:41], v[40:41], v[46:47]
	global_store_dwordx4 v[52:53], v[40:43], off offset:64 nt
	global_load_dwordx2 v[40:41], v[56:57], off offset:256
	s_waitcnt vmcnt(0)
	v_lshlrev_b32_e32 v42, 16, v40
	v_and_b32_e32 v43, 0xffff0000, v40
	v_lshlrev_b32_e32 v40, 16, v41
	v_and_b32_e32 v41, 0xffff0000, v41
	v_pk_add_f32 v[38:39], v[38:39], v[40:41]
	v_pk_add_f32 v[36:37], v[36:37], v[42:43]
	global_store_dwordx4 v[52:53], v[36:39], off offset:512 nt
	global_load_dwordx2 v[36:37], v[56:57], off offset:288
	s_waitcnt vmcnt(0)
	v_lshlrev_b32_e32 v42, 16, v36
	v_and_b32_e32 v43, 0xffff0000, v36
	v_lshlrev_b32_e32 v36, 16, v37
	v_and_b32_e32 v37, 0xffff0000, v37
	v_lshl_add_u64 v[38:39], v[140:141], 0, s[14:15]
	v_pk_add_f32 v[30:31], v[30:31], v[36:37]
	v_pk_add_f32 v[28:29], v[28:29], v[42:43]
	v_lshl_add_u64 v[40:41], v[38:39], 1, s[4:5]
	global_store_dwordx4 v[52:53], v[28:31], off offset:576 nt
	global_load_dwordx2 v[28:29], v[40:41], off
	v_lshl_add_u64 v[36:37], v[38:39], 2, s[82:83]
	s_waitcnt vmcnt(0)
	v_lshlrev_b32_e32 v38, 16, v28
	v_and_b32_e32 v39, 0xffff0000, v28
	v_lshlrev_b32_e32 v28, 16, v29
	v_and_b32_e32 v29, 0xffff0000, v29
	v_pk_add_f32 v[30:31], v[34:35], v[28:29]
	v_pk_add_f32 v[28:29], v[32:33], v[38:39]
	global_store_dwordx4 v[36:37], v[28:31], off nt
	global_load_dwordx2 v[28:29], v[40:41], off offset:32
	s_waitcnt vmcnt(0)
	v_lshlrev_b32_e32 v30, 16, v28
	v_and_b32_e32 v31, 0xffff0000, v28
	v_lshlrev_b32_e32 v28, 16, v29
	v_and_b32_e32 v29, 0xffff0000, v29
	v_pk_add_f32 v[26:27], v[26:27], v[28:29]
	v_pk_add_f32 v[24:25], v[24:25], v[30:31]
	global_store_dwordx4 v[36:37], v[24:27], off offset:64 nt
	global_load_dwordx2 v[24:25], v[40:41], off offset:256
	s_waitcnt vmcnt(0)
	v_lshlrev_b32_e32 v26, 16, v24
	v_and_b32_e32 v27, 0xffff0000, v24
	v_lshlrev_b32_e32 v24, 16, v25
	v_and_b32_e32 v25, 0xffff0000, v25
	v_pk_add_f32 v[22:23], v[22:23], v[24:25]
	v_pk_add_f32 v[20:21], v[20:21], v[26:27]
	global_store_dwordx4 v[36:37], v[20:23], off offset:512 nt
	global_load_dwordx2 v[20:21], v[40:41], off offset:288
	s_waitcnt vmcnt(0)
	v_lshlrev_b32_e32 v26, 16, v20
	v_and_b32_e32 v27, 0xffff0000, v20
	v_lshlrev_b32_e32 v20, 16, v21
	v_and_b32_e32 v21, 0xffff0000, v21
	v_lshl_add_u64 v[22:23], v[140:141], 0, s[16:17]
	v_pk_add_f32 v[14:15], v[14:15], v[20:21]
	v_pk_add_f32 v[12:13], v[12:13], v[26:27]
	v_lshl_add_u64 v[24:25], v[22:23], 1, s[4:5]
	global_store_dwordx4 v[36:37], v[12:15], off offset:576 nt
	global_load_dwordx2 v[12:13], v[24:25], off
	v_lshl_add_u64 v[20:21], v[22:23], 2, s[82:83]
	s_waitcnt vmcnt(0)
	v_lshlrev_b32_e32 v22, 16, v12
	v_and_b32_e32 v23, 0xffff0000, v12
	v_lshlrev_b32_e32 v12, 16, v13
	v_and_b32_e32 v13, 0xffff0000, v13
	v_pk_add_f32 v[14:15], v[18:19], v[12:13]
	v_pk_add_f32 v[12:13], v[16:17], v[22:23]
	global_store_dwordx4 v[20:21], v[12:15], off nt
	global_load_dwordx2 v[12:13], v[24:25], off offset:32
	s_waitcnt vmcnt(0)
	v_lshlrev_b32_e32 v14, 16, v12
	v_and_b32_e32 v15, 0xffff0000, v12
	v_lshlrev_b32_e32 v12, 16, v13
	v_and_b32_e32 v13, 0xffff0000, v13
	v_pk_add_f32 v[10:11], v[10:11], v[12:13]
	v_pk_add_f32 v[8:9], v[8:9], v[14:15]
	global_store_dwordx4 v[20:21], v[8:11], off offset:64 nt
	global_load_dwordx2 v[8:9], v[24:25], off offset:256
	s_waitcnt vmcnt(0)
	v_lshlrev_b32_e32 v10, 16, v8
	v_and_b32_e32 v11, 0xffff0000, v8
	v_lshlrev_b32_e32 v8, 16, v9
	v_and_b32_e32 v9, 0xffff0000, v9
	v_pk_add_f32 v[6:7], v[6:7], v[8:9]
	v_pk_add_f32 v[4:5], v[4:5], v[10:11]
	global_store_dwordx4 v[20:21], v[4:7], off offset:512 nt
	global_load_dwordx2 v[4:5], v[24:25], off offset:288
	s_waitcnt vmcnt(0)
	v_lshlrev_b32_e32 v6, 16, v4
	v_and_b32_e32 v7, 0xffff0000, v4
	v_lshlrev_b32_e32 v4, 16, v5
	v_and_b32_e32 v5, 0xffff0000, v5
	v_pk_add_f32 v[2:3], v[2:3], v[4:5]
	v_pk_add_f32 v[0:1], v[0:1], v[6:7]
	global_store_dwordx4 v[20:21], v[0:3], off offset:576 nt
	s_cbranch_vccnz .LBB0_1497
	s_andn2_b64 vcc, exec, s[2:3]
	s_cbranch_vccnz .LBB0_1496
	s_barrier
	s_branch .LBB0_1496
